# v12 + lazy pass-B publish: late WGs fold the pass-B release into their SSD-state release (one L2 writeback instead of two), early WGs publish without writeback
# speedup vs baseline: 1.0162x; 1.0162x over previous
; #define LAS __attribute__((address_space(3)))
; #define STAMP() do { if (PROBE_SEG >= 0 && bx == 0 && tid == 0) { tst[nst] = __builtin_amdgcn_s_memrealtime(); } ++nst; } while (0)
; #define BOTH(k) (IN(k) && IN((k) + 1))
; __global__ void __launch_bounds__(512, 2) hymba_fwd(Params p) {
;     ...
;         {
;             const int nfull = (MROWS / 256) * (NPAD / 256) + (MMEM / 256) * (1024 / 256) - ((MROWS / 256) * (NPAD / 256) + (MMEM / 256) * (1024 / 256)) / G * G;
;             const int first_idle = (nfull == 0) ? 0 : nfull, nidle = G - first_idle;
;             if (bx >= first_idle) {
;                 const int lane = tid & 63, wave = __builtin_amdgcn_readfirstlane(tid >> 6);
;                 tr_pipeline(p, (LAS float*)(lds + wave * 16896), lane, (bx - first_idle) * 8 + wave, nidle * 8, NITEMS_P0, NITEMS_ALL);
;                 cache_mem_convert(p, (bx - first_idle) * 512 + tid, nidle * 512);
;             }
;         }
;         if (BOTH(1)) GBAR(); STAMP();
.LBB0_576:
	s_cmp_eq_u32 s98, 1
	s_cbranch_scc0 .Lp1_bar
	s_mov_b32 s98, 2
	s_waitcnt vmcnt(0) lgkmcnt(0)
	s_barrier
	v_readlane_b32 s0, v254, 9
	s_cmpk_lt_i32 s0, 0x94
	s_cbranch_scc1 .Lp1_pub_skip
	v_cmp_eq_u32_e32 vcc, 0, v0
	s_and_saveexec_b64 s[0:1], vcc
	s_cbranch_execz .Lp1_pub_done
	v_mov_b32_e32 v1, 0x800
	v_mov_b32_e32 v2, 1
	global_atomic_add v1, v2, s[90:91]
	s_waitcnt vmcnt(0)

; #define STAMP() do { if (PROBE_SEG >= 0 && bx == 0 && tid == 0) { tst[nst] = __builtin_amdgcn_s_memrealtime(); } ++nst; } while (0)
; #define BOTH(k) (IN(k) && IN((k) + 1))
; __global__ void __launch_bounds__(512, 2) hymba_fwd(Params p) {
;     ...
;         if (BOTH(1)) GBAR(); STAMP();
;     }
;     if (IN(3)) { phase3<31>(p, lds, ctlw, 0); if (BOTH(3)) GBAR(); STAMP(); }
.Lp1_pub_skip:
	v_readlane_b32 s6, v254, 3
	v_readlane_b32 s7, v254, 4
	s_branch .LBB0_626

; #define PSTAMP(i) do { if (PROBE_SEG >= 20 && blockIdx.x == PROBE_BLK && threadIdx.x == 0) ((volatile LAS unsigned long long*)(ctlw + 32))[8 + (i)] = __builtin_amdgcn_s_memrealtime(); } while (0)
; #define QUEUE_LOOP(qi, total, ...) for (;;) { __syncthreads(); if (threadIdx.x == 0) ctlw[16] = __hip_atomic_fetch_add(qbase + 64 * (qi), 1u, __ATOMIC_RELAXED, __HIP_MEMORY_SCOPE_AGENT); \
;         __syncthreads(); const int u = (int)ctlw[16]; if (u >= (total)) break; __VA_ARGS__ }
; template <int MASK> __device__ __forceinline__ void phase3(const Params& p, LAS unsigned char* lds, volatile LAS unsigned* ctlw, int qset) {
;     ...
;     QUEUE_LOOP(0, U_SSDP, { ssd_state_unit<false>(p.ws, p.in[I_ALOG], p.in[I_SCONV], p.in[I_CONVW], p.in[I_CONVB], lds, u >> 5, (u >> 1) & 15, u & 1); })
;     QUEUE_LOOP(4, U_SSDSS, { ssd_state_unit<true>(p.ws, p.in[I_ALOG], p.in[I_SCONV], p.in[I_CONVW], p.in[I_CONVB], lds, u >> 1, 0, u & 1);
;         for (int hh = 0; hh < 4; ++hh)
;             ssd_out_unit<true>(p.ws, p.out, p.in[I_ALOG], p.in[I_DSKIP], p.in[I_SSDNW], p.in[I_SSM], p.in[I_SCONV], p.in[I_CONVW], p.in[I_CONVB], lds, u >> 1, 0, (u & 1) * 4 + hh); })
;     PSTAMP(5);
.LBB0_679:
	v_readlane_b32 s4, v254, 9
	s_sub_i32 s4, s4, 0x80
	s_min_u32 s99, s4, 16
	s_waitcnt vmcnt(0) lgkmcnt(0)
	s_barrier
	s_and_saveexec_b64 s[4:5], s[0:1]
	s_cbranch_execz .Lst_pub_done
	buffer_wbl2 sc1
	s_waitcnt vmcnt(0)
	v_mov_b32_e32 v2, 0xa00
	v_mov_b32_e32 v3, 1
	global_atomic_add v2, v3, s[90:91]
	global_atomic_add v2, v3, s[90:91] offset:-512
	s_waitcnt vmcnt(0)
